# v041 + NA: N1 bias wait ladders (14 counted waits) collapsed into one wait per tile
# baseline (speedup 1.0000x reference)
; #define A_DMAV(t, slot) do { const unsigned tt_ = (unsigned)((t) < NT ? (t) : NT - 1); \
;         glds16(dv_src[0] + (size_t)tt_ * 128u, (unsigned)__builtin_amdgcn_readfirstlane(lds_u + A_V0 + (slot) * A_VB + wid * 1024)); \
;         if (wid == 0) glds16(dv_src[1] + (size_t)tt_ * 128u, (unsigned)__builtin_amdgcn_readfirstlane(lds_u + A_V0 + (slot) * A_VB + 8 * 1024)); } while (0)
; template <bool NA>
; __device__ __forceinline__ void attn_unit(LAS unsigned char* lds, const bf16_t* Q, const bf16_t* Kg, const bf16_t* Kr, const bf16_t* Vt, bf16_t* O,
;                                           int h, int seqrow0, int q0, int t0, int NT, int rows, int g0, const float* rpb_h, int wid) {
;     ...
;     { A_DMAK(0, 0); A_DMAV(0, 0); A_DMAK(1, 1); A_DMAK(2, 2); A_DMAV(1, 1); }
;     asm volatile("s_waitcnt vmcnt(0)" ::: "memory");
;     __syncthreads();
;     f32x16 sA0, sA1, sB0, sB1; float tmA, tmB;
;     A_QK(sA0, sA1, 0);
;     A_MASK(sA0, sA1, 0);
;     tmA = rowmax32(sA0, sA1);
;     __syncthreads();
.LBB0_733:
	v_lshlrev_b32_e32 v0, 4, v4
	v_mul_u32_u24_e32 v2, 0x90, v3
	v_add3_u32 v173, v0, v2, 0
	s_waitcnt vmcnt(0)
	s_waitcnt lgkmcnt(0)
	s_barrier
	ds_read_b128 v[6:9], v173
	ds_read_b128 v[10:13], v173 offset:32
	s_waitcnt vmcnt(3) lgkmcnt(1)
	v_mfma_f32_32x32x16_bf16 v[44:59], v[6:9], v[146:149], 0
	s_cmp_gt_i32 s81, -1
	s_cselect_b64 s[38:39], -1, 0
	s_add_i32 s10, s10, s84
	v_sub_co_u32_e64 v2, s[6:7], s10, 4
	s_nop 0
	v_readfirstlane_b32 s8, v2
	s_min_u32 s1, s8, s1
	s_waitcnt vmcnt(2) lgkmcnt(0)
	v_mfma_f32_32x32x16_bf16 v[44:59], v[10:13], v[150:153], v[44:59]
	ds_read_b128 v[6:9], v173 offset:4608
	ds_read_b128 v[10:13], v173 offset:4640
	s_and_b64 s[6:7], s[6:7], exec
	s_cselect_b32 s33, 0, s1
	s_cmp_ge_u32 s79, s33
	s_cselect_b64 s[6:7], -1, 0
	s_add_i32 s88, s33, 8
	v_readlane_b32 s1, v244, 28
	s_waitcnt lgkmcnt(1)
	v_mfma_f32_32x32x16_bf16 v[28:43], v[6:9], v[146:149], 0
	s_cmp_lt_u32 s79, s88
	v_or_b32_e32 v5, s1, v3
	s_cselect_b64 s[8:9], -1, 0
	s_sub_i32 s1, s79, s10
	s_and_b64 s[6:7], s[6:7], s[8:9]
	s_mul_i32 s1, s1, 31
	s_addk_i32 s1, 0xe8
	s_waitcnt lgkmcnt(0)
	v_mfma_f32_32x32x16_bf16 v[28:43], v[10:13], v[150:153], v[28:43]
	ds_read_b128 v[6:9], v173 offset:64
	ds_read_b128 v[10:13], v173 offset:96
	s_and_b64 vcc, s[38:39], s[6:7]
	s_and_b64 s[6:7], vcc, exec
	s_cselect_b32 s1, s1, 15
	v_med3_u32 v2, v5, 8, 56
	v_sub_u32_e32 v5, s1, v5
	v_lshlrev_b32_e32 v5, 2, v5
	s_waitcnt vmcnt(1) lgkmcnt(1)
	v_mfma_f32_32x32x16_bf16 v[44:59], v[6:9], v[154:157], v[44:59]
	ds_read_b128 v[6:9], v173 offset:4672
	ds_read_b128 v[14:17], v173 offset:4704
	s_add_i32 s1, 0, 0x16400
	v_lshlrev_b32_e32 v172, 2, v4
	v_sub_u32_e32 v2, v172, v2
	v_add_u32_e32 v2, 8, v2
	v_cndmask_b32_e32 v4, v176, v2, vcc
	v_cmp_gt_u32_e32 vcc, 16, v4
	s_waitcnt lgkmcnt(1)
	v_mfma_f32_32x32x16_bf16 v[28:43], v[6:9], v[154:157], v[28:43]
	v_add3_u32 v6, s1, v5, v0
	ds_read_b32 v5, v6 offset:128
	s_waitcnt vmcnt(0)
	v_mfma_f32_32x32x16_bf16 v[44:59], v[10:13], v[158:161], v[44:59]
	s_waitcnt lgkmcnt(1)
	v_mfma_f32_32x32x16_bf16 v[28:43], v[14:17], v[158:161], v[28:43]
	v_mov_b32_e32 v17, 0xff800000
	v_mov_b32_e32 v16, 0xff800000
	ds_read2_b32 v[16:17], v6 offset0:0 offset1:1
	ds_read2_b32 v[18:19], v6 offset0:2 offset1:3
	ds_read2_b32 v[20:21], v6 offset0:8 offset1:9
	ds_read2_b32 v[22:23], v6 offset0:10 offset1:11
	ds_read2_b32 v[24:25], v6 offset0:16 offset1:17
	ds_read2_b32 v[26:27], v6 offset0:18 offset1:19
	ds_read2_b32 v[60:61], v6 offset0:24 offset1:25
	ds_read2_b32 v[62:63], v6 offset0:26 offset1:27
	s_waitcnt lgkmcnt(0)
	v_cmp_gt_u32_e32 vcc, 16, v4
	v_add_f32_e32 v16, v44, v16
	v_add_u32_e32 v207, 1, v4
	v_cndmask_b32_e32 v16, v177, v16, vcc
	v_cmp_gt_u32_e32 vcc, 16, v207
	v_add_f32_e32 v17, v45, v17
	v_add_u32_e32 v207, 2, v4
	v_cndmask_b32_e32 v17, v177, v17, vcc
	v_cmp_gt_u32_e32 vcc, 16, v207
	v_add_f32_e32 v18, v46, v18
	v_add_u32_e32 v207, 3, v4
	v_cndmask_b32_e32 v18, v177, v18, vcc
	v_cmp_gt_u32_e32 vcc, 16, v207
	v_add_f32_e32 v19, v47, v19
	v_add_u32_e32 v207, 8, v4
	v_cndmask_b32_e32 v19, v177, v19, vcc
	v_cmp_gt_u32_e32 vcc, 16, v207
	v_add_f32_e32 v20, v48, v20
	v_add_u32_e32 v207, 9, v4
	v_cndmask_b32_e32 v20, v177, v20, vcc
	v_cmp_gt_u32_e32 vcc, 16, v207
	v_add_f32_e32 v21, v49, v21
	v_add_u32_e32 v207, 10, v4
	v_cndmask_b32_e32 v21, v177, v21, vcc
	v_cmp_gt_u32_e32 vcc, 16, v207
	v_add_f32_e32 v22, v50, v22
	v_add_u32_e32 v207, 11, v4
	v_cndmask_b32_e32 v22, v177, v22, vcc
	v_cmp_gt_u32_e32 vcc, 16, v207
	v_add_f32_e32 v23, v51, v23
	s_nop 0
	v_cndmask_b32_e32 v23, v177, v23, vcc
	v_cmp_lt_u32_e32 vcc, s40, v4
	v_add_f32_e32 v24, v52, v24
	v_add_u32_e32 v207, 17, v4
	v_cndmask_b32_e32 v24, v177, v24, vcc
	v_cmp_gt_u32_e32 vcc, 16, v207
	v_add_f32_e32 v25, v53, v25
	v_add_u32_e32 v207, 18, v4
	v_cndmask_b32_e32 v25, v177, v25, vcc
	v_cmp_gt_u32_e32 vcc, 16, v207
	v_add_f32_e32 v26, v54, v26
	v_add_u32_e32 v207, 19, v4
	v_cndmask_b32_e32 v26, v177, v26, vcc
	v_cmp_gt_u32_e32 vcc, 16, v207
	v_add_f32_e32 v27, v55, v27
	v_add_u32_e32 v207, 24, v4
	v_cndmask_b32_e32 v27, v177, v27, vcc
	v_cmp_gt_u32_e32 vcc, 16, v207
	v_add_f32_e32 v60, v56, v60
	v_add_u32_e32 v207, 25, v4
	v_cndmask_b32_e32 v60, v177, v60, vcc
	v_cmp_gt_u32_e32 vcc, 16, v207
	v_add_f32_e32 v61, v57, v61
	v_add_u32_e32 v207, 26, v4
	v_cndmask_b32_e32 v61, v177, v61, vcc
	v_cmp_gt_u32_e32 vcc, 16, v207
	v_add_f32_e32 v62, v58, v62
	v_add_u32_e32 v207, 27, v4
	v_cndmask_b32_e32 v62, v177, v62, vcc
	v_cmp_gt_u32_e32 vcc, 16, v207
	v_add_f32_e32 v63, v59, v63
	s_nop 0
	v_cndmask_b32_e32 v63, v177, v63, vcc
	ds_read_b32 v7, v6 offset:132
	ds_read_b32 v8, v6 offset:136
	ds_read_b32 v9, v6 offset:140
	ds_read_b32 v10, v6 offset:160
	ds_read_b32 v11, v6 offset:164
	ds_read_b32 v12, v6 offset:168
	ds_read_b32 v13, v6 offset:172
	ds_read_b32 v14, v6 offset:192
	ds_read_b32 v15, v6 offset:196
	ds_read_b32 v44, v6 offset:200
	ds_read_b32 v45, v6 offset:204
	ds_read_b32 v46, v6 offset:224
	ds_read_b32 v47, v6 offset:228
	ds_read_b32 v48, v6 offset:232
	ds_read_b32 v49, v6 offset:236
	s_waitcnt lgkmcnt(0)
; __device__ __forceinline__ float max3f(float a, float b, float c) { float r; asm("v_max3_f32 %0, %1, %2, %3" : "=v"(r) : "v"(a), "v"(b), "v"(c)); return r; }
; __device__ __forceinline__ float rowmax32(const f32x16& p0, const f32x16& p1) {
;     float a = max3f(p0[0], p0[1], p1[0]), b = max3f(p0[2], p0[3], p1[1]); a = max3f(a, p1[2], p1[3]);
; #pragma unroll
;     for (int r = 4; r < 16; r += 4) { a = max3f(a, p0[r], p0[r + 1]); b = max3f(b, p0[r + 2], p0[r + 3]); a = max3f(a, p1[r], p1[r + 1]); b = max3f(b, p1[r + 2], p1[r + 3]); }
;     const float m = fmaxf(a, b);
;     auto rr = __builtin_amdgcn_permlane32_swap(__float_as_uint(m), __float_as_uint(m), false, false);
;     return fmaxf(__uint_as_float(rr[0]), __uint_as_float(rr[1]));
; }
	v_add_f32_e32 v6, v29, v7
	v_add_f32_e32 v7, v30, v8
	v_add_f32_e32 v8, v31, v9
	v_add_f32_e32 v9, v32, v10
	v_add_f32_e32 v10, v33, v11
	v_add_u32_e32 v33, 33, v4
	v_cmp_gt_u32_e32 vcc, 16, v33
	v_add_u32_e32 v33, 34, v4
	v_cmp_gt_u32_e64 s[6:7], 16, v33
	v_add_u32_e32 v33, 35, v4
	v_cmp_gt_u32_e64 s[8:9], 16, v33
	v_add_u32_e32 v33, 40, v4
	v_cmp_gt_u32_e64 s[10:11], 16, v33
	v_add_u32_e32 v33, 41, v4
	v_cmp_gt_u32_e64 s[12:13], 16, v33
	v_add_u32_e32 v33, 42, v4
	v_cmp_gt_u32_e64 s[14:15], 16, v33
	v_add_u32_e32 v33, 43, v4
	v_cmp_gt_u32_e64 s[16:17], 16, v33
	v_add_u32_e32 v33, 49, v4
	v_cmp_gt_u32_e64 s[18:19], 16, v33
	v_add_u32_e32 v33, 50, v4
	v_cmp_gt_u32_e64 s[20:21], 16, v33
	v_add_u32_e32 v33, 51, v4
	v_cmp_gt_u32_e64 s[22:23], 16, v33
	v_add_u32_e32 v33, 56, v4
	v_cmp_gt_u32_e64 s[24:25], 16, v33
	v_add_u32_e32 v33, 57, v4
	v_cmp_gt_u32_e64 s[26:27], 16, v33
	v_add_u32_e32 v33, 58, v4
	v_cmp_gt_u32_e64 s[28:29], 16, v33
	v_add_u32_e32 v33, 59, v4
	v_and_b32_e32 v4, -16, v4
	v_add_f32_e32 v5, v28, v5
	v_cmp_eq_u32_e64 s[36:37], s41, v4
	v_cmp_eq_u32_e64 s[34:35], s42, v4
	v_cndmask_b32_e64 v82, v177, v7, s[6:7]
	v_cndmask_b32_e64 v80, v177, v5, s[36:37]
	v_max3_f32 v4, v16, v17, v80
	v_cndmask_b32_e64 v81, v177, v8, s[8:9]
	v_max3_f32 v4, v4, v82, v81
	v_cndmask_b32_e32 v95, v177, v6, vcc
	v_max3_f32 v5, v18, v19, v95
	v_add_f32_e32 v11, v34, v12
	v_add_f32_e32 v12, v35, v13
	v_max3_f32 v4, v4, v20, v21
	v_max3_f32 v5, v5, v22, v23
	v_cndmask_b32_e64 v84, v177, v9, s[10:11]
	v_cndmask_b32_e64 v89, v177, v10, s[12:13]
	v_max3_f32 v4, v4, v84, v89
	v_cndmask_b32_e64 v86, v177, v11, s[14:15]
	v_cndmask_b32_e64 v83, v177, v12, s[16:17]
	v_max3_f32 v5, v5, v86, v83
	v_add_f32_e32 v13, v36, v14
	v_add_f32_e32 v14, v37, v15
	v_add_f32_e32 v15, v38, v44
	v_add_f32_e32 v28, v39, v45
	v_max3_f32 v4, v4, v24, v25
	v_max3_f32 v5, v5, v26, v27
	v_cndmask_b32_e64 v88, v177, v13, s[34:35]
	v_cndmask_b32_e64 v91, v177, v14, s[18:19]
	v_max3_f32 v4, v4, v88, v91
	v_cndmask_b32_e64 v90, v177, v15, s[20:21]
	v_cndmask_b32_e64 v85, v177, v28, s[22:23]
	v_max3_f32 v5, v5, v90, v85
	v_add_f32_e32 v29, v40, v46
	v_add_f32_e32 v30, v41, v47
	v_add_f32_e32 v31, v42, v48
	v_add_f32_e32 v32, v43, v49
	v_cmp_gt_u32_e64 s[30:31], 16, v33
	v_max3_f32 v4, v4, v60, v61
	v_max3_f32 v5, v5, v62, v63
	v_cndmask_b32_e64 v92, v177, v29, s[24:25]
	v_cndmask_b32_e64 v93, v177, v30, s[26:27]
	v_max3_f32 v4, v4, v92, v93
	v_cndmask_b32_e64 v94, v177, v31, s[28:29]
	v_cndmask_b32_e64 v87, v177, v32, s[30:31]
	v_max3_f32 v5, v5, v94, v87
	v_max_f32_e32 v4, v4, v5
	v_mov_b32_e32 v5, v4
	s_nop 1
	v_permlane32_swap_b32_e32 v4, v5
	s_and_b64 vcc, exec, s[38:39]
	s_barrier
	s_cbranch_vccz .LBB0_868
	v_max_f32_e32 v180, v4, v5
	v_and_b32_e32 v4, -16, v2
	s_movk_i32 s1, 0xffef
	v_cmp_eq_u32_e64 s[8:9], s41, v4
	v_add_u32_e32 v5, 1, v2
	v_cmp_lt_u32_e64 s[40:41], s1, v2
	s_movk_i32 s1, 0xffd0
	v_cmp_gt_u32_e64 s[10:11], 16, v5
	v_add_u32_e32 v5, 33, v2
	v_cmp_eq_u32_e64 s[42:43], s1, v4
	v_add_u32_e32 v4, 17, v2
	v_cmp_gt_u32_e64 s[12:13], 16, v5
	v_add_u32_e32 v5, 2, v2
	v_cmp_gt_u32_e64 s[44:45], 16, v4
	v_add_u32_e32 v4, 49, v2
	v_cmp_gt_u32_e64 s[14:15], 16, v5
	v_add_u32_e32 v5, 34, v2
	v_cmp_gt_u32_e64 s[46:47], 16, v4
	v_add_u32_e32 v4, 18, v2
	v_cmp_gt_u32_e64 s[16:17], 16, v5
	v_add_u32_e32 v5, 3, v2
	v_cmp_gt_u32_e64 s[48:49], 16, v4
	v_add_u32_e32 v4, 50, v2
	v_cmp_gt_u32_e64 s[18:19], 16, v5
	v_add_u32_e32 v5, 35, v2
	v_cmp_gt_u32_e64 s[50:51], 16, v4
	v_add_u32_e32 v4, 19, v2
	v_cmp_gt_u32_e64 s[20:21], 16, v5
	v_add_u32_e32 v5, 8, v2
	v_cmp_gt_u32_e64 s[52:53], 16, v4
	v_add_u32_e32 v4, 51, v2
	v_cmp_gt_u32_e64 s[22:23], 16, v5
	v_add_u32_e32 v5, 40, v2
	v_cmp_gt_u32_e64 s[54:55], 16, v4
	v_add_u32_e32 v4, 24, v2
	v_cmp_gt_u32_e64 s[24:25], 16, v5
	v_add_u32_e32 v5, 9, v2
	v_cmp_gt_u32_e64 s[56:57], 16, v4
	v_add_u32_e32 v4, 56, v2
	v_cmp_gt_u32_e64 s[26:27], 16, v5
	v_add_u32_e32 v5, 41, v2
	v_cmp_gt_u32_e64 s[58:59], 16, v4
	v_add_u32_e32 v4, 25, v2
	v_cmp_gt_u32_e64 s[28:29], 16, v5
	v_add_u32_e32 v5, 10, v2
	v_cmp_gt_u32_e64 s[60:61], 16, v4
	v_add_u32_e32 v4, 57, v2
	v_cmp_gt_u32_e64 s[30:31], 16, v5
	v_add_u32_e32 v5, 42, v2
	v_cmp_gt_u32_e64 s[62:63], 16, v4
	v_add_u32_e32 v4, 26, v2
	v_cmp_gt_u32_e64 s[34:35], 16, v5
	v_add_u32_e32 v5, 11, v2
	v_cmp_gt_u32_e64 s[64:65], 16, v4
	v_add_u32_e32 v4, 58, v2
	v_cmp_gt_u32_e64 s[6:7], 16, v2
	v_cmp_gt_u32_e64 s[36:37], 16, v5
	v_add_u32_e32 v5, 43, v2
	v_cmp_gt_u32_e64 s[66:67], 16, v4
	v_add_u32_e32 v4, 27, v2
	v_add_u32_e32 v2, 59, v2
	s_mul_i32 s1, s79, 0x7c
	v_cmp_gt_u32_e64 s[70:71], 16, v2
	v_add_u32_e32 v0, s1, v0
	v_lshlrev_b32_e32 v2, 2, v3
	v_sub_u32_e32 v0, v0, v2
	s_mulk_i32 s0, 0x1f0
	v_subrev_u32_e32 v0, s0, v0
	v_readlane_b32 s0, v244, 29
	v_mov_b32_e32 v14, v1
	v_mov_b32_e32 v15, v1
	v_cmp_gt_u32_e64 s[38:39], 16, v5
	v_cmp_gt_u32_e64 s[68:69], 16, v4
	v_add_u32_e32 v179, s0, v0
	v_mov_b32_e32 v0, v1
	v_mov_b32_e32 v2, v1
	v_mov_b32_e32 v3, v1
	v_mov_b32_e32 v4, v1
	v_mov_b32_e32 v5, v1
	v_mov_b32_e32 v6, v1
	v_mov_b32_e32 v7, v1
	v_mov_b32_e32 v8, v1
	v_mov_b32_e32 v9, v1
	v_mov_b32_e32 v10, v1
	v_mov_b32_e32 v11, v1
	v_mov_b32_e32 v12, v1
	v_mov_b32_e32 v13, v1
	v_mov_b32_e32 v178, 0
	v_mov_b64_e32 v[58:59], v[14:15]
	v_mov_b64_e32 v[42:43], v[14:15]
	s_sub_i32 s83, s79, s33
	s_mov_b32 s1, 4
	v_mov_b64_e32 v[56:57], v[12:13]
	v_mov_b64_e32 v[54:55], v[10:11]
	v_mov_b64_e32 v[52:53], v[8:9]
	v_mov_b64_e32 v[50:51], v[6:7]
	v_mov_b64_e32 v[48:49], v[4:5]
	v_mov_b64_e32 v[46:47], v[2:3]
	v_mov_b64_e32 v[44:45], v[0:1]
	v_mov_b64_e32 v[40:41], v[12:13]
	v_mov_b64_e32 v[38:39], v[10:11]
	v_mov_b64_e32 v[36:37], v[8:9]
	v_mov_b64_e32 v[34:35], v[6:7]
	v_mov_b64_e32 v[32:33], v[4:5]
	v_mov_b64_e32 v[30:31], v[2:3]
	v_mov_b64_e32 v[28:29], v[0:1]
	v_mov_b32_e32 v2, 0
	v_mov_b32_e32 v112, 0
	v_mov_b32_e32 v113, v178
	v_mov_b32_e32 v114, v178
	v_mov_b32_e32 v115, v178
	v_mov_b32_e32 v116, v178
	v_mov_b32_e32 v117, v178
	v_mov_b32_e32 v118, v178
	v_mov_b32_e32 v119, v178
	v_mov_b32_e32 v120, v178
	v_mov_b32_e32 v121, v178
	v_mov_b32_e32 v122, v178
	v_mov_b32_e32 v123, v178
	v_mov_b32_e32 v124, v178
	v_mov_b32_e32 v125, v178
	v_mov_b32_e32 v126, v178
	v_mov_b32_e32 v127, v178
	s_branch .LBB0_768

; __device__ __forceinline__ float max3f(float a, float b, float c) { float r; asm("v_max3_f32 %0, %1, %2, %3" : "=v"(r) : "v"(a), "v"(b), "v"(c)); return r; }
; __device__ __forceinline__ float rowmax32(const f32x16& p0, const f32x16& p1) {
;     float a = max3f(p0[0], p0[1], p1[0]), b = max3f(p0[2], p0[3], p1[1]); a = max3f(a, p1[2], p1[3]);
; #pragma unroll
;     for (int r = 4; r < 16; r += 4) { a = max3f(a, p0[r], p0[r + 1]); b = max3f(b, p0[r + 2], p0[r + 3]); a = max3f(a, p1[r], p1[r + 1]); b = max3f(b, p1[r + 2], p1[r + 3]); }
;     const float m = fmaxf(a, b);
;     auto rr = __builtin_amdgcn_permlane32_swap(__float_as_uint(m), __float_as_uint(m), false, false);
;     return fmaxf(__uint_as_float(rr[0]), __uint_as_float(rr[1]));
; }
.LBB0_779:
.LBB0_780:
.LBB0_781:
.LBB0_782:
	s_add_i32 s87, s1, -4
	s_add_i32 s0, s74, -3
	s_cmp_ge_i32 s0, s33
	s_cselect_b64 s[94:95], -1, 0
	s_cmp_lt_i32 s0, s88
	s_cselect_b64 s[96:97], -1, 0
	s_and_b64 s[94:95], s[94:95], s[96:97]
	s_add_i32 s0, s1, -3
	s_cmp_lt_i32 s87, s81
	s_cselect_b64 s[96:97], -1, 0
	s_and_b64 vcc, s[94:95], s[96:97]
	s_andn2_b64 vcc, exec, vcc
	s_cbranch_vccnz .LBB0_817
	s_and_b32 s90, s0, 3
	s_mulk_i32 s90, 0x3400
	v_add_u32_e32 v0, s90, v173
	ds_read_b128 v[64:67], v0 offset:4608
	ds_read_b128 v[68:71], v0
	ds_read_b128 v[72:75], v0 offset:32
	ds_read_b128 v[220:223], v0 offset:4640
	ds_read_b128 v[224:227], v0 offset:64
	ds_read_b128 v[228:231], v0 offset:4672
	ds_read_b128 v[232:235], v0 offset:96
	ds_read_b128 v[236:239], v0 offset:4704
	s_waitcnt lgkmcnt(7)
	v_mfma_f32_32x32x16_bf16 v[96:111], v[64:67], v[146:149], v[112:127]
	s_waitcnt lgkmcnt(6)
	v_mfma_f32_32x32x16_bf16 v[130:145], v[68:71], v[146:149], v[112:127]
	s_waitcnt lgkmcnt(5)
	v_mfma_f32_32x32x16_bf16 v[130:145], v[72:75], v[150:153], v[130:145]
	s_waitcnt lgkmcnt(4)
	v_mfma_f32_32x32x16_bf16 v[96:111], v[220:223], v[150:153], v[96:111]
	s_waitcnt lgkmcnt(3)
	v_mfma_f32_32x32x16_bf16 v[130:145], v[224:227], v[154:157], v[130:145]
	s_waitcnt lgkmcnt(2)
	v_mfma_f32_32x32x16_bf16 v[96:111], v[228:231], v[154:157], v[96:111]
	s_waitcnt lgkmcnt(1)
	v_mfma_f32_32x32x16_bf16 v[130:145], v[232:235], v[158:161], v[130:145]
	s_waitcnt lgkmcnt(0)
	v_mfma_f32_32x32x16_bf16 v[96:111], v[236:239], v[158:161], v[96:111]
	ds_read_b32 v0, v179 offset:128
	ds_read2_b32 v[64:65], v179 offset0:0 offset1:1
	ds_read2_b32 v[66:67], v179 offset0:2 offset1:3
	ds_read2_b32 v[68:69], v179 offset0:8 offset1:9
	ds_read2_b32 v[70:71], v179 offset0:10 offset1:11
	ds_read2_b32 v[72:73], v179 offset0:16 offset1:17
	ds_read2_b32 v[74:75], v179 offset0:18 offset1:19
	ds_read2_b32 v[76:77], v179 offset0:24 offset1:25
	ds_read2_b32 v[78:79], v179 offset0:26 offset1:27
	s_waitcnt lgkmcnt(0)
	v_add_f32_e32 v64, v130, v64
	v_cndmask_b32_e64 v64, v177, v64, s[6:7]
	v_add_f32_e32 v65, v131, v65
	v_cndmask_b32_e64 v65, v177, v65, s[10:11]
	v_add_f32_e32 v66, v132, v66
	v_cndmask_b32_e64 v66, v177, v66, s[14:15]
	v_add_f32_e32 v67, v133, v67
	v_cndmask_b32_e64 v67, v177, v67, s[18:19]
	v_add_f32_e32 v68, v134, v68
	v_cndmask_b32_e64 v68, v177, v68, s[22:23]
	v_add_f32_e32 v69, v135, v69
	v_cndmask_b32_e64 v69, v177, v69, s[26:27]
	v_add_f32_e32 v70, v136, v70
	v_cndmask_b32_e64 v70, v177, v70, s[30:31]
	v_add_f32_e32 v71, v137, v71
	v_cndmask_b32_e64 v71, v177, v71, s[36:37]
	v_add_f32_e32 v72, v138, v72
	v_cndmask_b32_e64 v72, v177, v72, s[40:41]
	v_add_f32_e32 v73, v139, v73
	v_cndmask_b32_e64 v73, v177, v73, s[44:45]
	v_add_f32_e32 v74, v140, v74
	v_cndmask_b32_e64 v74, v177, v74, s[48:49]
	v_add_f32_e32 v75, v141, v75
	v_cndmask_b32_e64 v75, v177, v75, s[52:53]
	v_add_f32_e32 v76, v142, v76
	v_cndmask_b32_e64 v76, v177, v76, s[56:57]
	v_add_f32_e32 v77, v143, v77
	v_cndmask_b32_e64 v77, v177, v77, s[60:61]
	v_add_f32_e32 v78, v144, v78
	v_cndmask_b32_e64 v78, v177, v78, s[64:65]
	v_add_f32_e32 v79, v145, v79
	v_cndmask_b32_e64 v79, v177, v79, s[68:69]
	ds_read_b32 v3, v179 offset:132
	ds_read_b32 v129, v179 offset:136
	ds_read_b32 v130, v179 offset:140
	ds_read_b32 v131, v179 offset:160
	ds_read_b32 v132, v179 offset:164
	ds_read_b32 v133, v179 offset:168
	ds_read_b32 v134, v179 offset:172
	ds_read_b32 v135, v179 offset:192
	ds_read_b32 v136, v179 offset:196
	ds_read_b32 v137, v179 offset:200
	ds_read_b32 v138, v179 offset:204
	ds_read_b32 v139, v179 offset:224
	ds_read_b32 v140, v179 offset:228
	ds_read_b32 v142, v179 offset:232
	ds_read_b32 v141, v179 offset:236
	s_waitcnt lgkmcnt(0)
	v_add_f32_e32 v0, v96, v0
	v_cndmask_b32_e64 v96, v177, v0, s[8:9]
	v_add_f32_e32 v0, v97, v3
	v_cndmask_b32_e64 v97, v177, v0, s[12:13]
	v_add_f32_e32 v0, v98, v129
	v_cndmask_b32_e64 v98, v177, v0, s[16:17]
	v_add_f32_e32 v0, v99, v130
	v_cndmask_b32_e64 v99, v177, v0, s[20:21]
	v_add_f32_e32 v0, v100, v131
	v_cndmask_b32_e64 v100, v177, v0, s[24:25]
	v_add_f32_e32 v0, v101, v132
	v_cndmask_b32_e64 v101, v177, v0, s[28:29]
	v_add_f32_e32 v0, v102, v133
	v_cndmask_b32_e64 v102, v177, v0, s[34:35]
	v_add_f32_e32 v0, v103, v134
	v_cndmask_b32_e64 v103, v177, v0, s[38:39]
	v_add_f32_e32 v0, v104, v135
	v_cndmask_b32_e64 v104, v177, v0, s[42:43]
	v_add_f32_e32 v0, v105, v136
	v_cndmask_b32_e64 v105, v177, v0, s[46:47]
	v_add_f32_e32 v0, v106, v137
	v_cndmask_b32_e64 v106, v177, v0, s[50:51]
	v_add_f32_e32 v0, v107, v138
	v_cndmask_b32_e64 v107, v177, v0, s[54:55]
	v_add_f32_e32 v0, v108, v139
	v_cndmask_b32_e64 v108, v177, v0, s[58:59]
	v_add_f32_e32 v0, v109, v140
	v_cndmask_b32_e64 v109, v177, v0, s[62:63]
	v_add_f32_e32 v0, v110, v142
	v_cndmask_b32_e64 v110, v177, v0, s[66:67]
	v_add_f32_e32 v0, v111, v141
	v_cndmask_b32_e64 v111, v177, v0, s[70:71]
	v_max3_f32 v0, v64, v65, v96
	v_max3_f32 v3, v66, v67, v97
	v_max3_f32 v0, v0, v98, v99
	v_max3_f32 v3, v3, v70, v71
	v_max3_f32 v0, v0, v68, v69
	v_max3_f32 v3, v3, v102, v103
	v_max3_f32 v0, v0, v100, v101
	v_max3_f32 v3, v3, v74, v75
	v_max3_f32 v0, v0, v72, v73
	v_max3_f32 v3, v3, v106, v107
	v_max3_f32 v0, v0, v104, v105
	v_max3_f32 v3, v3, v78, v79
	v_max3_f32 v0, v0, v76, v77
	v_max3_f32 v3, v3, v110, v111
	v_max3_f32 v0, v0, v108, v109
	v_max_f32_e32 v0, v0, v3
	v_mov_b32_e32 v3, v0
	s_nop 1
	v_permlane32_swap_b32_e32 v0, v3
	v_max_f32_e32 v3, v0, v3
	s_and_b64 vcc, exec, s[72:73]
	s_cbranch_vccz .LBB0_818

; __device__ __forceinline__ float max3f(float a, float b, float c) { float r; asm("v_max3_f32 %0, %1, %2, %3" : "=v"(r) : "v"(a), "v"(b), "v"(c)); return r; }
; __device__ __forceinline__ float rowmax32(const f32x16& p0, const f32x16& p1) {
;     float a = max3f(p0[0], p0[1], p1[0]), b = max3f(p0[2], p0[3], p1[1]); a = max3f(a, p1[2], p1[3]);
; #pragma unroll
;     for (int r = 4; r < 16; r += 4) { a = max3f(a, p0[r], p0[r + 1]); b = max3f(b, p0[r + 2], p0[r + 3]); a = max3f(a, p1[r], p1[r + 1]); b = max3f(b, p1[r + 2], p1[r + 3]); }
;     const float m = fmaxf(a, b);
;     auto rr = __builtin_amdgcn_permlane32_swap(__float_as_uint(m), __float_as_uint(m), false, false);
;     return fmaxf(__uint_as_float(rr[0]), __uint_as_float(rr[1]));
; }
.LBB0_829:
	s_add_i32 s74, s74, -2
	s_cmp_ge_i32 s74, s33
	s_cselect_b64 s[90:91], -1, 0
	s_cmp_lt_i32 s74, s88
	s_cselect_b64 s[94:95], -1, 0
	s_and_b64 s[90:91], s[90:91], s[94:95]
	s_cmp_le_i32 s85, s81
	s_cselect_b64 s[94:95], -1, 0
	s_and_b64 s[90:91], s[90:91], s[94:95]
	s_andn2_b64 vcc, exec, s[90:91]
	s_cbranch_vccnz .LBB0_863
	s_mulk_i32 s77, 0x3400
	v_add_u32_e32 v0, s77, v173
	ds_read_b128 v[4:7], v0 offset:4608
	ds_read_b128 v[8:11], v0
	ds_read_b128 v[12:15], v0 offset:32
	ds_read_b128 v[220:223], v0 offset:4640
	ds_read_b128 v[224:227], v0 offset:64
	ds_read_b128 v[228:231], v0 offset:4672
	ds_read_b128 v[232:235], v0 offset:96
	ds_read_b128 v[236:239], v0 offset:4704
	v_mov_b32_e32 v17, 0xff800000
	v_mov_b32_e32 v16, 0xff800000
	s_waitcnt lgkmcnt(6)
	v_mfma_f32_32x32x16_bf16 v[80:95], v[8:11], v[146:149], v[112:127]
	v_mfma_f32_32x32x16_bf16 v[130:145], v[4:7], v[146:149], v[112:127]
	s_waitcnt lgkmcnt(5)
	v_mfma_f32_32x32x16_bf16 v[80:95], v[12:15], v[150:153], v[80:95]
	s_waitcnt lgkmcnt(4)
	v_mfma_f32_32x32x16_bf16 v[130:145], v[220:223], v[150:153], v[130:145]
	s_waitcnt lgkmcnt(3)
	v_mfma_f32_32x32x16_bf16 v[80:95], v[224:227], v[154:157], v[80:95]
	s_waitcnt lgkmcnt(2)
	v_mfma_f32_32x32x16_bf16 v[130:145], v[228:231], v[154:157], v[130:145]
	s_waitcnt lgkmcnt(1)
	v_mfma_f32_32x32x16_bf16 v[80:95], v[232:235], v[158:161], v[80:95]
	s_waitcnt lgkmcnt(0)
	v_mfma_f32_32x32x16_bf16 v[130:145], v[236:239], v[158:161], v[130:145]
	ds_read_b32 v0, v179 offset:252
	ds_read2_b32 v[16:17], v179 offset0:31 offset1:32
	ds_read2_b32 v[18:19], v179 offset0:33 offset1:34
	ds_read2_b32 v[20:21], v179 offset0:39 offset1:40
	ds_read2_b32 v[22:23], v179 offset0:41 offset1:42
	ds_read2_b32 v[24:25], v179 offset0:47 offset1:48
	ds_read2_b32 v[26:27], v179 offset0:49 offset1:50
	ds_read2_b32 v[60:61], v179 offset0:55 offset1:56
	ds_read2_b32 v[62:63], v179 offset0:57 offset1:58
	s_waitcnt lgkmcnt(0)
	v_add_f32_e32 v16, v80, v16
	v_cndmask_b32_e64 v16, v177, v16, s[6:7]
	v_add_f32_e32 v17, v81, v17
	v_cndmask_b32_e64 v17, v177, v17, s[10:11]
	v_add_f32_e32 v18, v82, v18
	v_cndmask_b32_e64 v18, v177, v18, s[14:15]
	v_add_f32_e32 v19, v83, v19
	v_cndmask_b32_e64 v19, v177, v19, s[18:19]
	v_add_f32_e32 v20, v84, v20
	v_cndmask_b32_e64 v20, v177, v20, s[22:23]
	v_add_f32_e32 v21, v85, v21
	v_cndmask_b32_e64 v21, v177, v21, s[26:27]
	v_add_f32_e32 v22, v86, v22
	v_cndmask_b32_e64 v22, v177, v22, s[30:31]
	v_add_f32_e32 v23, v87, v23
	v_cndmask_b32_e64 v23, v177, v23, s[36:37]
	v_add_f32_e32 v24, v88, v24
	v_cndmask_b32_e64 v24, v177, v24, s[40:41]
	v_add_f32_e32 v25, v89, v25
	v_cndmask_b32_e64 v25, v177, v25, s[44:45]
	v_add_f32_e32 v26, v90, v26
	v_cndmask_b32_e64 v26, v177, v26, s[48:49]
	v_add_f32_e32 v27, v91, v27
	v_cndmask_b32_e64 v27, v177, v27, s[52:53]
	v_add_f32_e32 v60, v92, v60
	v_cndmask_b32_e64 v60, v177, v60, s[56:57]
	v_add_f32_e32 v61, v93, v61
	v_cndmask_b32_e64 v61, v177, v61, s[60:61]
	v_add_f32_e32 v62, v94, v62
	v_cndmask_b32_e64 v62, v177, v62, s[64:65]
	v_add_f32_e32 v63, v95, v63
	v_cndmask_b32_e64 v63, v177, v63, s[68:69]
	ds_read_b32 v4, v179 offset:256
	ds_read_b32 v5, v179 offset:260
	ds_read_b32 v6, v179 offset:264
	ds_read_b32 v7, v179 offset:284
	ds_read_b32 v8, v179 offset:288
	ds_read_b32 v9, v179 offset:292
	ds_read_b32 v10, v179 offset:296
	ds_read_b32 v11, v179 offset:316
	ds_read_b32 v12, v179 offset:320
	ds_read_b32 v13, v179 offset:324
	ds_read_b32 v14, v179 offset:328
	ds_read_b32 v15, v179 offset:348
	ds_read_b32 v80, v179 offset:352
	ds_read_b32 v82, v179 offset:356
	ds_read_b32 v81, v179 offset:360
	s_waitcnt lgkmcnt(0)
	v_add_f32_e32 v0, v130, v0
	v_add_f32_e32 v4, v131, v4
	v_add_f32_e32 v5, v132, v5
	v_add_f32_e32 v6, v133, v6
	v_add_f32_e32 v87, v143, v80
	v_cndmask_b32_e64 v80, v177, v0, s[8:9]
	v_max3_f32 v0, v16, v17, v80
	v_add_f32_e32 v94, v144, v82
	v_add_f32_e32 v128, v145, v81
	v_cndmask_b32_e64 v82, v177, v5, s[16:17]
	v_cndmask_b32_e64 v81, v177, v6, s[20:21]
	v_max3_f32 v0, v0, v82, v81
	v_cndmask_b32_e64 v95, v177, v4, s[12:13]
	v_max3_f32 v4, v18, v19, v95
	v_add_f32_e32 v7, v134, v7
	v_add_f32_e32 v8, v135, v8
	v_add_f32_e32 v9, v136, v9
	v_add_f32_e32 v10, v137, v10
	v_max3_f32 v0, v0, v20, v21
	v_max3_f32 v4, v4, v22, v23
	v_cndmask_b32_e64 v84, v177, v7, s[24:25]
	v_cndmask_b32_e64 v89, v177, v8, s[28:29]
	v_max3_f32 v0, v0, v84, v89
	v_cndmask_b32_e64 v86, v177, v9, s[34:35]
	v_cndmask_b32_e64 v83, v177, v10, s[38:39]
	v_max3_f32 v4, v4, v86, v83
	v_add_f32_e32 v11, v138, v11
	v_add_f32_e32 v12, v139, v12
	v_add_f32_e32 v13, v140, v13
	v_add_f32_e32 v14, v141, v14
	v_max3_f32 v0, v0, v24, v25
	v_max3_f32 v4, v4, v26, v27
	v_cndmask_b32_e64 v88, v177, v11, s[42:43]
	v_cndmask_b32_e64 v91, v177, v12, s[46:47]
	v_max3_f32 v0, v0, v88, v91
	v_cndmask_b32_e64 v90, v177, v13, s[50:51]
	v_cndmask_b32_e64 v85, v177, v14, s[54:55]
	v_max3_f32 v4, v4, v90, v85
	v_add_f32_e32 v15, v142, v15
	v_max3_f32 v0, v0, v60, v61
	v_max3_f32 v4, v4, v62, v63
	v_cndmask_b32_e64 v92, v177, v15, s[58:59]
	v_cndmask_b32_e64 v93, v177, v87, s[62:63]
	v_max3_f32 v0, v0, v92, v93
	v_cndmask_b32_e64 v94, v177, v94, s[66:67]
	v_cndmask_b32_e64 v87, v177, v128, s[70:71]
	v_max3_f32 v4, v4, v94, v87
	v_max_f32_e32 v0, v0, v4
	v_mov_b32_e32 v4, v0
	s_nop 1
	v_permlane32_swap_b32_e32 v0, v4
	v_max_f32_e32 v180, v0, v4
